# barrier-last-leader-fans-out-release-to-all-XCC-gen-words
# speedup vs baseline: 1.0278x; 1.0074x over previous
.LBB0_625:
	s_or_b64 exec, exec, s[36:37]
	v_readlane_b32 s4, v253, 3
	v_readlane_b32 s5, v253, 4
	s_orn2_b64 s[36:37], s[38:39], exec
	s_nop 0
	v_mov_b64_e32 v[0:1], s[4:5]
	s_branch .LBB0_626
.Lrel_all:
	s_or_b64 exec, exec, s[30:31]
	v_readlane_b32 s4, v253, 3
	v_readlane_b32 s5, v253, 4
	s_nop 0
	s_add_u32 s4, s4, 0x2200
	s_addc_u32 s5, s5, 0
	s_nop 4
	global_atomic_add v97, v226, s[4:5]
	global_atomic_add v97, v226, s[4:5] offset:256
	global_atomic_add v97, v226, s[4:5] offset:512
	global_atomic_add v97, v226, s[4:5] offset:768
	global_atomic_add v97, v226, s[4:5] offset:1024
	global_atomic_add v97, v226, s[4:5] offset:1280
	global_atomic_add v97, v226, s[4:5] offset:1536
	global_atomic_add v97, v226, s[4:5] offset:1792
	global_atomic_add v97, v226, s[4:5] offset:2048
	global_atomic_add v97, v226, s[4:5] offset:2304
	global_atomic_add v97, v226, s[4:5] offset:2560
	global_atomic_add v97, v226, s[4:5] offset:2816
	global_atomic_add v97, v226, s[4:5] offset:3072
	global_atomic_add v97, v226, s[4:5] offset:3328
	global_atomic_add v97, v226, s[4:5] offset:3584
	global_atomic_add v97, v226, s[4:5] offset:3840

.LBB0_628:
	s_or_b64 exec, exec, s[30:31]
	s_mov_b64 s[30:31], exec
	v_mbcnt_lo_u32_b32 v0, s30, 0
	v_mbcnt_hi_u32_b32 v0, s31, v0
	v_cmp_eq_u32_e32 vcc, 0, v0
	s_waitcnt vmcnt(0)
	buffer_inv sc1
	s_and_saveexec_b64 s[36:37], vcc
	s_cbranch_execz .LBB0_23
	s_bcnt1_i32_b64 s2, s[30:31]
	v_readlane_b32 s4, v253, 39
	v_mov_b32_e32 v0, s2
	v_readlane_b32 s5, v253, 40
	s_nop 4
	s_branch .LBB0_23
